# P9 65th-panel tail: LN2 scale/shift loads for all four chunks issued before the variance reduction instead of a load/wait/store ladder
# speedup vs baseline: 1.0052x; 1.0052x over previous
.LBB0_1249:
	v_add_u32_e32 v0, 0xffffc000, v182
	v_ashrrev_i32_e32 v1, 31, v0
	v_lshlrev_b64 v[0:1], 12, v[0:1]
	v_lshl_add_u64 v[42:43], v[36:37], 0, v[0:1]
	v_add_co_u32_e32 v44, vcc, 0x100000, v42
	global_load_dwordx4 v[78:81], v[42:43], off
	s_nop 0
	v_addc_co_u32_e32 v45, vcc, 0, v43, vcc
	v_add_co_u32_e32 v46, vcc, 0x200000, v42
	global_load_dwordx4 v[82:85], v[44:45], off
	s_nop 0
	v_addc_co_u32_e32 v47, vcc, 0, v43, vcc
	v_add_co_u32_e32 v48, vcc, 0x300000, v42
	global_load_dwordx4 v[86:89], v[46:47], off
	s_nop 0
	v_addc_co_u32_e32 v49, vcc, 0, v43, vcc
	v_add_co_u32_e32 v50, vcc, 0x400000, v42
	global_load_dwordx4 v[90:93], v[48:49], off
	s_nop 0
	v_addc_co_u32_e32 v51, vcc, 0, v43, vcc
	v_add_co_u32_e32 v52, vcc, 0x500000, v42
	global_load_dwordx4 v[94:97], v[50:51], off
	s_nop 0
	v_addc_co_u32_e32 v53, vcc, 0, v43, vcc
	v_add_co_u32_e32 v54, vcc, 0x600000, v42
	global_load_dwordx4 v[98:101], v[52:53], off
	s_nop 0
	v_addc_co_u32_e32 v55, vcc, 0, v43, vcc
	v_add_co_u32_e32 v56, vcc, 0x700000, v42
	global_load_dwordx4 v[102:105], v[54:55], off
	s_nop 0
	v_addc_co_u32_e32 v57, vcc, 0, v43, vcc
	v_add_co_u32_e32 v58, vcc, 0x800000, v42
	global_load_dwordx4 v[106:109], v[56:57], off
	s_nop 0
	v_addc_co_u32_e32 v59, vcc, 0, v43, vcc
	v_add_co_u32_e32 v60, vcc, 0x900000, v42
	global_load_dwordx4 v[110:113], v[58:59], off
	s_nop 0
	v_addc_co_u32_e32 v61, vcc, 0, v43, vcc
	v_add_co_u32_e32 v62, vcc, 0xa00000, v42
	global_load_dwordx4 v[114:117], v[60:61], off
	s_nop 0
	v_addc_co_u32_e32 v63, vcc, 0, v43, vcc
	global_load_dwordx4 v[118:121], v[62:63], off
	v_add_co_u32_e32 v64, vcc, 0xb00000, v42
	s_waitcnt vmcnt(9)
	v_pk_add_f32 v[80:81], v[80:81], v[84:85]
	v_addc_co_u32_e32 v65, vcc, 0, v43, vcc
	global_load_dwordx4 v[122:125], v[64:65], off
	global_load_dwordx2 v[66:67], v[38:39], off
	global_load_dwordx4 v[0:3], v[30:31], off
	global_load_dwordx4 v[4:7], v[42:43], off offset:1024
	global_load_dwordx4 v[8:11], v[44:45], off offset:1024
	global_load_dwordx4 v[12:15], v[46:47], off offset:1024
	global_load_dwordx4 v[16:19], v[48:49], off offset:1024
	global_load_dwordx4 v[20:23], v[50:51], off offset:1024
	global_load_dwordx4 v[24:27], v[52:53], off offset:1024
	global_load_dwordx4 v[126:129], v[54:55], off offset:1024
	global_load_dwordx4 v[130:133], v[56:57], off offset:1024
	global_load_dwordx4 v[134:137], v[58:59], off offset:1024
	global_load_dwordx4 v[138:141], v[60:61], off offset:1024
	v_pk_add_f32 v[78:79], v[78:79], v[82:83]
	s_waitcnt vmcnt(21)
	v_pk_add_f32 v[80:81], v[80:81], v[88:89]
	v_pk_add_f32 v[78:79], v[78:79], v[86:87]
	global_load_dwordx2 v[170:171], v[38:39], off offset:512
	v_cmp_lt_i32_e32 vcc, v72, v71
	s_waitcnt vmcnt(21)
	v_pk_add_f32 v[82:83], v[80:81], v[92:93]
	v_pk_add_f32 v[86:87], v[78:79], v[90:91]
	global_load_dwordx4 v[78:81], v[62:63], off offset:1024
	s_waitcnt vmcnt(21)
	v_pk_add_f32 v[88:89], v[82:83], v[96:97]
	v_pk_add_f32 v[90:91], v[86:87], v[94:95]
	global_load_dwordx4 v[82:85], v[64:65], off offset:1024
	s_waitcnt vmcnt(21)
	v_pk_add_f32 v[92:93], v[88:89], v[100:101]
	v_pk_add_f32 v[90:91], v[90:91], v[98:99]
	global_load_dwordx4 v[86:89], v[30:31], off offset:1024
	s_waitcnt vmcnt(21)
	v_pk_add_f32 v[92:93], v[92:93], v[104:105]
	v_pk_add_f32 v[90:91], v[90:91], v[102:103]
	s_waitcnt vmcnt(20)
	v_pk_add_f32 v[92:93], v[92:93], v[108:109]
	v_pk_add_f32 v[90:91], v[90:91], v[106:107]
	s_waitcnt vmcnt(19)
	v_pk_add_f32 v[92:93], v[92:93], v[112:113]
	v_pk_add_f32 v[90:91], v[90:91], v[110:111]
	s_waitcnt vmcnt(18)
	v_pk_add_f32 v[98:99], v[92:93], v[116:117]
	v_pk_add_f32 v[102:103], v[90:91], v[114:115]
	global_load_dwordx4 v[90:93], v[42:43], off offset:2048
	global_load_dwordx4 v[94:97], v[44:45], off offset:2048
	s_waitcnt vmcnt(19)
	v_pk_add_f32 v[106:107], v[98:99], v[120:121]
	v_pk_add_f32 v[110:111], v[102:103], v[118:119]
	global_load_dwordx4 v[98:101], v[46:47], off offset:2048
	global_load_dwordx4 v[102:105], v[48:49], off offset:2048
	s_waitcnt vmcnt(20)
	v_pk_add_f32 v[158:159], v[106:107], v[124:125]
	s_waitcnt vmcnt(19)
	v_lshlrev_b32_e32 v146, 16, v66
	v_and_b32_e32 v147, 0xffff0000, v66
	v_lshlrev_b32_e32 v66, 16, v67
	v_and_b32_e32 v67, 0xffff0000, v67
	v_pk_add_f32 v[150:151], v[110:111], v[122:123]
	s_waitcnt vmcnt(18)
	v_pk_fma_f32 v[0:1], v[146:147], s[8:9], v[0:1] op_sel_hi:[1,0,1]
	v_pk_fma_f32 v[2:3], v[66:67], s[8:9], v[2:3] op_sel_hi:[1,0,1]
	v_pk_add_f32 v[0:1], v[150:151], v[0:1]
	v_pk_add_f32 v[2:3], v[158:159], v[2:3]
	v_mov_b32_e32 v66, v0
	v_mov_b32_e32 v67, v3
	v_pk_mov_b32 v[158:159], v[0:1], v[2:3] op_sel:[1,0]
	global_load_dwordx4 v[106:109], v[50:51], off offset:2048
	global_load_dwordx4 v[110:113], v[52:53], off offset:2048
	global_load_dwordx4 v[114:117], v[54:55], off offset:2048
	global_load_dwordx4 v[118:121], v[56:57], off offset:2048
	global_load_dwordx2 v[172:173], v[38:39], off offset:1024
	global_load_dwordx2 v[174:175], v[38:39], off offset:1536
	global_load_dwordx4 v[122:125], v[58:59], off offset:2048
	global_load_dwordx4 v[142:145], v[60:61], off offset:2048
	global_load_dwordx4 v[146:149], v[62:63], off offset:2048
	global_load_dwordx4 v[150:153], v[64:65], off offset:2048
	global_load_dwordx4 v[154:157], v[30:31], off offset:2048
	v_pk_add_f32 v[66:67], v[66:67], v[158:159]
	global_load_dwordx4 v[158:161], v[42:43], off offset:3072
	s_nop 0
	global_load_dwordx4 v[42:45], v[44:45], off offset:3072
	s_waitcnt vmcnt(29)
	v_pk_add_f32 v[6:7], v[6:7], v[10:11]
	global_load_dwordx4 v[162:165], v[46:47], off offset:3072
	global_load_dwordx4 v[166:169], v[50:51], off offset:3072
	v_pk_add_f32 v[4:5], v[4:5], v[8:9]
	global_load_dwordx4 v[46:49], v[48:49], off offset:3072
	s_waitcnt vmcnt(31)
	v_pk_add_f32 v[6:7], v[6:7], v[14:15]
	global_load_dwordx4 v[50:53], v[52:53], off offset:3072
	v_pk_add_f32 v[4:5], v[4:5], v[12:13]
	global_load_dwordx4 v[12:15], v[54:55], off offset:3072
	s_waitcnt vmcnt(32)
	v_pk_add_f32 v[6:7], v[6:7], v[18:19]
	v_pk_add_f32 v[4:5], v[4:5], v[16:17]
	global_load_dwordx4 v[16:19], v[58:59], off offset:3072
	s_waitcnt vmcnt(32)
	v_pk_add_f32 v[6:7], v[6:7], v[22:23]
	global_load_dwordx4 v[54:57], v[56:57], off offset:3072
	v_pk_add_f32 v[4:5], v[4:5], v[20:21]
	global_load_dwordx4 v[58:61], v[60:61], off offset:3072
	s_waitcnt vmcnt(33)
	v_pk_add_f32 v[6:7], v[6:7], v[26:27]
	global_load_dwordx4 v[20:23], v[62:63], off offset:3072
	v_pk_add_f32 v[4:5], v[4:5], v[24:25]
	global_load_dwordx4 v[62:65], v[64:65], off offset:3072
	s_waitcnt vmcnt(34)
	v_pk_add_f32 v[4:5], v[4:5], v[126:127]
	global_load_dwordx4 v[24:27], v[30:31], off offset:3072
	s_waitcnt vmcnt(34)
	v_pk_add_f32 v[4:5], v[4:5], v[130:131]
	v_pk_add_f32 v[6:7], v[6:7], v[128:129]
	s_waitcnt vmcnt(33)
	v_pk_add_f32 v[4:5], v[4:5], v[134:135]
	v_pk_add_f32 v[6:7], v[6:7], v[132:133]
	s_waitcnt vmcnt(32)
	v_pk_add_f32 v[4:5], v[4:5], v[138:139]
	v_pk_add_f32 v[6:7], v[6:7], v[136:137]
	s_waitcnt vmcnt(30)
	v_pk_add_f32 v[4:5], v[4:5], v[78:79]
	v_lshlrev_b32_e32 v8, 16, v170
	v_and_b32_e32 v9, 0xffff0000, v170
	v_pk_add_f32 v[6:7], v[6:7], v[140:141]
	s_waitcnt vmcnt(29)
	v_pk_add_f32 v[4:5], v[4:5], v[82:83]
	s_waitcnt vmcnt(28)
	v_pk_fma_f32 v[8:9], v[8:9], s[8:9], v[86:87] op_sel_hi:[1,0,1]
	v_pk_add_f32 v[6:7], v[6:7], v[80:81]
	v_pk_add_f32 v[4:5], v[4:5], v[8:9]
	v_lshlrev_b32_e32 v8, 16, v171
	v_and_b32_e32 v9, 0xffff0000, v171
	v_pk_add_f32 v[6:7], v[6:7], v[84:85]
	v_pk_fma_f32 v[8:9], v[8:9], s[8:9], v[88:89] op_sel_hi:[1,0,1]
	v_add_f32_e32 v28, v66, v67
	v_pk_add_f32 v[6:7], v[6:7], v[8:9]
	v_mov_b32_e32 v8, v4
	v_mov_b32_e32 v9, v7
	v_pk_mov_b32 v[10:11], v[4:5], v[6:7] op_sel:[1,0]
	v_add_f32_e32 v66, 0, v28
	v_pk_add_f32 v[8:9], v[8:9], v[10:11]
	s_waitcnt vmcnt(26)
	v_pk_add_f32 v[10:11], v[90:91], v[94:95]
	v_pk_add_f32 v[78:79], v[8:9], v[8:9] op_sel:[0,1] op_sel_hi:[1,0]
	v_pk_add_f32 v[8:9], v[92:93], v[96:97]
	s_waitcnt vmcnt(25)
	v_pk_add_f32 v[10:11], v[10:11], v[98:99]
	v_pk_add_f32 v[8:9], v[8:9], v[100:101]
	s_waitcnt vmcnt(24)
	v_pk_add_f32 v[10:11], v[10:11], v[102:103]
	v_pk_add_f32 v[8:9], v[8:9], v[104:105]
	s_waitcnt vmcnt(23)
	v_pk_add_f32 v[10:11], v[10:11], v[106:107]
	v_pk_add_f32 v[8:9], v[8:9], v[108:109]
	s_waitcnt vmcnt(22)
	v_pk_add_f32 v[10:11], v[10:11], v[110:111]
	v_pk_add_f32 v[8:9], v[8:9], v[112:113]
	s_waitcnt vmcnt(21)
	v_pk_add_f32 v[10:11], v[10:11], v[114:115]
	v_pk_add_f32 v[8:9], v[8:9], v[116:117]
	s_waitcnt vmcnt(20)
	v_pk_add_f32 v[10:11], v[10:11], v[118:119]
	v_pk_add_f32 v[8:9], v[8:9], v[120:121]
	s_waitcnt vmcnt(11)
	v_pk_add_f32 v[42:43], v[158:159], v[42:43]
	v_pk_add_f32 v[44:45], v[160:161], v[44:45]
	s_waitcnt vmcnt(10)
	v_pk_add_f32 v[42:43], v[42:43], v[162:163]
	v_pk_add_f32 v[44:45], v[44:45], v[164:165]
	v_pk_add_f32 v[8:9], v[8:9], v[124:125]
	s_waitcnt vmcnt(8)
	v_pk_add_f32 v[42:43], v[42:43], v[46:47]
	v_pk_add_f32 v[44:45], v[44:45], v[48:49]
	v_pk_add_f32 v[42:43], v[42:43], v[166:167]
	v_pk_add_f32 v[10:11], v[10:11], v[122:123]
	s_waitcnt vmcnt(7)
	v_pk_add_f32 v[42:43], v[42:43], v[50:51]
	v_pk_add_f32 v[44:45], v[44:45], v[168:169]
	s_waitcnt vmcnt(6)
	v_pk_add_f32 v[12:13], v[42:43], v[12:13]
	v_pk_add_f32 v[8:9], v[8:9], v[144:145]
	v_pk_add_f32 v[10:11], v[10:11], v[142:143]
	v_pk_add_f32 v[44:45], v[44:45], v[52:53]
	s_waitcnt vmcnt(4)
	v_pk_add_f32 v[12:13], v[12:13], v[54:55]
	v_pk_add_f32 v[8:9], v[8:9], v[148:149]
	v_pk_add_f32 v[10:11], v[10:11], v[146:147]
	v_pk_add_f32 v[14:15], v[44:45], v[14:15]
	v_pk_add_f32 v[12:13], v[12:13], v[16:17]
	v_pk_add_f32 v[80:81], v[8:9], v[152:153]
	v_pk_add_f32 v[8:9], v[10:11], v[150:151]
	v_lshlrev_b32_e32 v10, 16, v172
	v_and_b32_e32 v11, 0xffff0000, v172
	v_pk_add_f32 v[14:15], v[14:15], v[56:57]
	s_waitcnt vmcnt(3)
	v_pk_add_f32 v[12:13], v[12:13], v[58:59]
	v_pk_fma_f32 v[10:11], v[10:11], s[8:9], v[154:155] op_sel_hi:[1,0,1]
	v_pk_add_f32 v[14:15], v[14:15], v[18:19]
	s_waitcnt vmcnt(2)
	v_pk_add_f32 v[12:13], v[12:13], v[20:21]
	v_lshlrev_b32_e32 v16, 16, v174
	v_and_b32_e32 v17, 0xffff0000, v174
	v_pk_add_f32 v[8:9], v[8:9], v[10:11]
	v_lshlrev_b32_e32 v10, 16, v173
	v_and_b32_e32 v11, 0xffff0000, v173
	v_pk_add_f32 v[14:15], v[14:15], v[60:61]
	s_waitcnt vmcnt(1)
	v_pk_add_f32 v[12:13], v[12:13], v[62:63]
	s_waitcnt vmcnt(0)
	v_pk_fma_f32 v[16:17], v[16:17], s[8:9], v[24:25] op_sel_hi:[1,0,1]
	v_pk_fma_f32 v[10:11], v[10:11], s[8:9], v[156:157] op_sel_hi:[1,0,1]
	v_pk_add_f32 v[14:15], v[14:15], v[22:23]
	v_pk_add_f32 v[12:13], v[12:13], v[16:17]
	v_lshlrev_b32_e32 v16, 16, v175
	v_and_b32_e32 v17, 0xffff0000, v175
	v_pk_add_f32 v[10:11], v[80:81], v[10:11]
	v_pk_add_f32 v[14:15], v[14:15], v[64:65]
	v_pk_fma_f32 v[16:17], v[16:17], s[8:9], v[26:27] op_sel_hi:[1,0,1]
	v_pk_add_f32 v[80:81], v[8:9], v[8:9] op_sel:[0,1] op_sel_hi:[1,0]
	v_pk_add_f32 v[82:83], v[10:11], v[10:11] op_sel:[1,0] op_sel_hi:[0,1]
	v_pk_add_f32 v[14:15], v[14:15], v[16:17]
	v_mov_b32_e32 v67, v12
	v_mov_b32_e32 v79, v13
	v_mov_b32_e32 v81, v15
	v_mov_b32_e32 v83, v14
	v_pk_add_f32 v[16:17], v[66:67], v[78:79]
	v_pk_add_f32 v[18:19], v[80:81], v[82:83]
	s_nop 0
	v_pk_add_f32 v[16:17], v[16:17], v[18:19]
	s_nop 0
	v_add_f32_e32 v16, v16, v17
	v_cndmask_b32_e32 v17, v70, v72, vcc
	v_lshlrev_b32_e32 v28, 2, v17
	ds_bpermute_b32 v17, v28, v16
	v_cmp_lt_i32_e32 vcc, v73, v71
	s_waitcnt lgkmcnt(0)
	v_add_f32_e32 v16, v16, v17
	v_cndmask_b32_e32 v17, v70, v73, vcc
	v_lshlrev_b32_e32 v44, 2, v17
	ds_bpermute_b32 v17, v44, v16
	v_cmp_lt_i32_e32 vcc, v74, v71
	s_waitcnt lgkmcnt(0)
	v_add_f32_e32 v16, v16, v17
	v_cndmask_b32_e32 v17, v70, v74, vcc
	v_lshlrev_b32_e32 v45, 2, v17
	ds_bpermute_b32 v17, v45, v16
	v_cmp_lt_i32_e32 vcc, v75, v71
	s_waitcnt lgkmcnt(0)
	v_add_f32_e32 v16, v16, v17
	v_cndmask_b32_e32 v17, v70, v75, vcc
	v_lshlrev_b32_e32 v46, 2, v17
	ds_bpermute_b32 v17, v46, v16
	v_cmp_lt_i32_e32 vcc, v76, v71
	s_waitcnt lgkmcnt(0)
	v_add_f32_e32 v16, v16, v17
	v_cndmask_b32_e32 v17, v70, v76, vcc
	v_lshlrev_b32_e32 v47, 2, v17
	ds_bpermute_b32 v17, v47, v16
	v_cmp_lt_i32_e32 vcc, v77, v71
	s_waitcnt lgkmcnt(0)
	v_add_f32_e32 v16, v16, v17
	v_cndmask_b32_e32 v17, v70, v77, vcc
	v_lshlrev_b32_e32 v48, 2, v17
	ds_bpermute_b32 v17, v48, v16
	s_waitcnt lgkmcnt(0)
	v_add_f32_e32 v22, v16, v17
	v_fmamk_f32 v1, v22, 0xba800000, v1
	v_fmac_f32_e32 v0, 0xba800000, v22
	v_fmamk_f32 v3, v22, 0xba800000, v3
	v_fmac_f32_e32 v2, 0xba800000, v22
	v_pk_mul_f32 v[16:17], v[2:3], v[2:3]
	v_pk_mul_f32 v[18:19], v[0:1], v[0:1]
	v_fmamk_f32 v5, v22, 0xba800000, v5
	v_pk_mov_b32 v[20:21], v[18:19], v[16:17] op_sel:[1,0]
	v_mov_b32_e32 v19, v17
	v_pk_add_f32 v[16:17], v[20:21], v[18:19]
	v_fmac_f32_e32 v4, 0xba800000, v22
	v_fmamk_f32 v7, v22, 0xba800000, v7
	v_fmac_f32_e32 v6, 0xba800000, v22
	v_pk_add_f32 v[24:25], v[16:17], v[16:17] op_sel_hi:[0,1]
	v_pk_mul_f32 v[16:17], v[6:7], v[6:7]
	v_pk_mul_f32 v[18:19], v[4:5], v[4:5]
	v_fmac_f32_e32 v8, 0xba800000, v22
	v_pk_mov_b32 v[20:21], v[18:19], v[16:17] op_sel:[1,0]
	v_mov_b32_e32 v19, v17
	v_pk_add_f32 v[16:17], v[20:21], v[18:19]
	v_fmamk_f32 v9, v22, 0xba800000, v9
	v_pk_add_f32 v[26:27], v[16:17], v[16:17] op_sel_hi:[0,1]
	v_mul_f32_e32 v16, v8, v8
	v_fmac_f32_e32 v10, 0xba800000, v22
	v_pk_fma_f32 v[16:17], v[8:9], v[8:9], v[16:17] op_sel_hi:[1,1,0]
	v_fmamk_f32 v11, v22, 0xba800000, v11
	v_mul_f32_e32 v16, v10, v10
	v_pk_fma_f32 v[18:19], v[10:11], v[10:11], v[16:17] op_sel_hi:[1,1,0]
	v_fmamk_f32 v13, v22, 0xba800000, v13
	v_fmac_f32_e32 v12, 0xba800000, v22
	v_mul_f32_e32 v16, v12, v12
	v_mul_f32_e32 v18, v13, v13
	v_fmamk_f32 v15, v22, 0xba800000, v15
	v_fmac_f32_e32 v14, 0xba800000, v22
	v_pk_add_f32 v[42:43], v[16:17], v[18:19]
	global_load_dwordx4 v[16:19], v[32:33], off
	global_load_dwordx4 v[20:23], v[34:35], off
	global_load_dwordx4 v[190:193], v[32:33], off offset:1024
	global_load_dwordx4 v[194:197], v[34:35], off offset:1024
	global_load_dwordx4 v[198:201], v[32:33], off offset:2048
	global_load_dwordx4 v[202:205], v[34:35], off offset:2048
	global_load_dwordx4 v[206:209], v[32:33], off offset:3072
	global_load_dwordx4 v[210:213], v[34:35], off offset:3072
	v_mul_f32_e32 v24, v14, v14
	v_mul_f32_e32 v26, v15, v15
	v_pk_add_f32 v[24:25], v[24:25], v[26:27]
	s_nop 0
	v_pk_add_f32 v[24:25], v[42:43], v[24:25]
	s_nop 0
	v_add_f32_e32 v24, v24, v25
	ds_bpermute_b32 v25, v28, v24
	s_waitcnt lgkmcnt(0)
	v_add_f32_e32 v24, v24, v25
	ds_bpermute_b32 v25, v44, v24
	s_waitcnt lgkmcnt(0)
	v_add_f32_e32 v24, v24, v25
	ds_bpermute_b32 v25, v45, v24
	s_waitcnt lgkmcnt(0)
	v_add_f32_e32 v24, v24, v25
	ds_bpermute_b32 v25, v46, v24
	s_waitcnt lgkmcnt(0)
	v_add_f32_e32 v24, v24, v25
	ds_bpermute_b32 v25, v47, v24
	s_waitcnt lgkmcnt(0)
	v_add_f32_e32 v24, v24, v25
	ds_bpermute_b32 v25, v48, v24
	s_waitcnt lgkmcnt(0)
	v_add_f32_e32 v24, v24, v25
	v_fmamk_f32 v24, v24, 0x3a800000, v68
	v_mul_f32_e32 v25, 0x4f800000, v24
	v_cmp_gt_f32_e32 vcc, s13, v24
	s_nop 1
	v_cndmask_b32_e32 v24, v24, v25, vcc
	v_sqrt_f32_e32 v25, v24
	s_nop 0
	v_add_u32_e32 v26, -1, v25
	v_fma_f32 v27, -v26, v25, v24
	v_cmp_ge_f32_e64 s[0:1], 0, v27
	v_add_u32_e32 v27, 1, v25
	s_nop 0
	v_cndmask_b32_e64 v26, v25, v26, s[0:1]
	v_fma_f32 v25, -v27, v25, v24
	v_cmp_lt_f32_e64 s[0:1], 0, v25
	s_nop 1
	v_cndmask_b32_e64 v25, v26, v27, s[0:1]
	v_mul_f32_e32 v26, 0x37800000, v25
	v_cndmask_b32_e32 v25, v25, v26, vcc
	v_cmp_class_f32_e32 vcc, v24, v69
	s_nop 1
	v_cndmask_b32_e32 v24, v25, v24, vcc
	v_div_scale_f32 v25, s[0:1], v24, v24, 1.0
	v_rcp_f32_e32 v26, v25
	s_nop 0
	v_fma_f32 v27, -v25, v26, 1.0
	v_fmac_f32_e32 v26, v27, v26
	v_div_scale_f32 v27, vcc, 1.0, v24, 1.0
	v_mul_f32_e32 v28, v27, v26
	v_fma_f32 v42, -v25, v28, v27
	v_fmac_f32_e32 v28, v42, v26
	v_fma_f32 v25, -v25, v28, v27
	v_div_fmas_f32 v25, v25, v26, v28
	v_div_fixup_f32 v24, v25, v24, 1.0
	v_pk_mul_f32 v[0:1], v[0:1], v[24:25] op_sel_hi:[1,0]
	v_pk_mul_f32 v[2:3], v[2:3], v[24:25] op_sel_hi:[1,0]
	v_lshl_add_u64 v[26:27], v[40:41], 0, v[186:187]
	s_waitcnt vmcnt(0)
	v_pk_fma_f32 v[2:3], v[18:19], v[2:3], v[22:23]
	v_pk_fma_f32 v[0:1], v[16:17], v[0:1], v[20:21]
	global_store_dwordx4 v[26:27], v[0:3], off
	s_nop 0
	s_nop 0
	s_nop 0
	v_pk_mul_f32 v[6:7], v[6:7], v[24:25] op_sel_hi:[1,0]
	v_pk_mul_f32 v[4:5], v[4:5], v[24:25] op_sel_hi:[1,0]
	v_pk_mul_f32 v[10:11], v[10:11], v[24:25] op_sel_hi:[1,0]
	v_pk_mul_f32 v[8:9], v[8:9], v[24:25] op_sel_hi:[1,0]
	s_nop 0
	v_pk_fma_f32 v[0:1], v[190:191], v[4:5], v[194:195]
	v_pk_fma_f32 v[2:3], v[192:193], v[6:7], v[196:197]
	global_store_dwordx4 v[26:27], v[0:3], off offset:1024
	s_nop 0
	s_nop 0
	s_nop 0
	s_nop 0
	v_pk_fma_f32 v[0:1], v[198:199], v[8:9], v[202:203]
	v_pk_fma_f32 v[2:3], v[200:201], v[10:11], v[204:205]
	global_store_dwordx4 v[26:27], v[0:3], off offset:2048
	s_nop 0
	s_nop 0
	s_nop 0
	v_pk_mul_f32 v[8:9], v[14:15], v[24:25] op_sel_hi:[1,0]
	v_pk_mul_f32 v[10:11], v[12:13], v[24:25] op_sel_hi:[1,0]
	s_nop 0
	v_pk_fma_f32 v[2:3], v[208:209], v[8:9], v[212:213]
	v_pk_fma_f32 v[0:1], v[206:207], v[10:11], v[210:211]
	global_store_dwordx4 v[26:27], v[0:3], off offset:3072
	s_branch .LBB0_1243
